# GATES pair tiles: per-XCD queue = 64 pair tickets (one per WG) then 64 single tickets
# speedup vs baseline: 1.0073x; 1.0073x over previous
.LBB0_256:
	s_or_b64 exec, exec, s[8:9]
	s_mov_b64 s[8:9], src_shared_base
	v_mov_b32_e32 v121, s9
	s_waitcnt lgkmcnt(0)
	s_barrier
	flat_load_dword v0, v[120:121] sc0 sc1
	s_waitcnt vmcnt(0)
	s_mov_b32 s63, 0
	s_mov_b32 s62, 0
	s_mov_b32 s61, 0
	s_cmp_eq_u32 s98, 0
	s_cbranch_scc1 .Lgq_skip1
	v_readfirstlane_b32 s60, v0
	s_cmp_lt_u32 s60, 64
	s_cbranch_scc0 .Lgd_s1
	s_mov_b32 s63, 1
	s_mul_hi_u32 s13, s60, 0x2aaaaaab
	s_mul_i32 s8, s13, 6
	s_sub_i32 s8, s60, s8
	s_lshl_b32 s13, s13, 1
	s_branch .Lgd_e1
.Lgd_s1:
	s_add_i32 s8, s60, 0xffffffc0
	s_cmp_lt_u32 s8, 64
	s_cbranch_scc0 .Lgd_x1
	s_cmp_lt_u32 s8, 4
	s_cbranch_scc0 .Lgd_t1
	s_and_b32 s13, s8, 1
	s_add_i32 s13, s13, 20
	s_lshr_b32 s8, s8, 1
	s_add_i32 s8, s8, 4
	s_branch .Lgd_e1
.Lgd_t1:
	s_add_i32 s8, s8, -4
	s_mul_hi_u32 s13, s8, 0x2aaaaaab
	s_mul_i32 s9, s13, 6
	s_sub_i32 s8, s8, s9
	s_add_i32 s13, s13, 22

.LBB0_263:
	s_or_b64 exec, exec, s[18:19]
	s_mov_b64 s[18:19], src_shared_base
	v_mov_b32_e32 v121, s19
	s_waitcnt lgkmcnt(0)
	s_barrier
	flat_load_dword v103, v[120:121] sc0 sc1
	s_waitcnt vmcnt(0)
	s_mov_b32 s61, 0
	s_cmp_eq_u32 s98, 0
	s_cbranch_scc1 .Lgq_skip2
	v_readfirstlane_b32 s60, v103
	s_cmp_lt_u32 s60, 64
	s_cbranch_scc0 .Lgd_s2
	s_mov_b32 s61, 1
	s_mul_hi_u32 s13, s60, 0x2aaaaaab
	s_mul_i32 s18, s13, 6
	s_sub_i32 s18, s60, s18
	s_lshl_b32 s13, s13, 1
	s_branch .Lgd_e2
.Lgd_s2:
	s_add_i32 s18, s60, 0xffffffc0
	s_cmp_lt_u32 s18, 64
	s_cbranch_scc0 .Lgd_x2
	s_cmp_lt_u32 s18, 4
	s_cbranch_scc0 .Lgd_t2
	s_and_b32 s13, s18, 1
	s_add_i32 s13, s13, 20
	s_lshr_b32 s18, s18, 1
	s_add_i32 s18, s18, 4
	s_branch .Lgd_e2
.Lgd_t2:
	s_add_i32 s18, s18, -4
	s_mul_hi_u32 s13, s18, 0x2aaaaaab
	s_mul_i32 s19, s13, 6
	s_sub_i32 s18, s18, s19
	s_add_i32 s13, s13, 22
